# ffn-in epilogue: row-scale loads issued before the K loop so the epilogue no longer drains vmcnt
# baseline (speedup 1.0000x reference)
; template <class Epi, class SchedT, class HookT = NoHook>
; __device__ __forceinline__ void gemm_phase(LAS unsigned char* lds, const SchedT& S, const Epi& E, int wave_, const HookT& H = HookT()) {
;     ...
;     Unit cur, nxt; int ui = 0;
;     if (!S.next(0, cur)) return;
;     f32x4 acc[2][2][4][2];
; #pragma unroll
;     for (int a = 0; a < 2; ++a)
; #pragma unroll
;         for (int b = 0; b < 2; ++b)
; #pragma unroll
;             for (int m = 0; m < 4; ++m)
; #pragma unroll
;                 for (int n = 0; n < 2; ++n) acc[a][b][m][n] = (f32x4){0.f, 0.f, 0.f, 0.f};
; __device__ __forceinline__ void load_rs(float (&rs)[2][4], const float* ssx, int row0) {
; #pragma unroll
;     for (int ai = 0; ai < 2; ++ai)
; #pragma unroll
;         for (int m = 0; m < 4; ++m) rs[ai][m] = ssx[row0 + ai * 128 + m * 16];
.LBB0_1194:
	s_add_u32 s100, s2, s36
	s_addc_u32 s101, s3, 0
	v_lshl_add_u32 v240, s18, 8, v143
	v_ashrrev_i32_e32 v241, 31, v240
	v_lshl_add_u64 v[240:241], v[240:241], 2, s[100:101]
	global_load_dword v232, v[240:241], off
	global_load_dword v233, v[240:241], off offset:64
	global_load_dword v234, v[240:241], off offset:128
	global_load_dword v235, v[240:241], off offset:192
	global_load_dword v236, v[240:241], off offset:512
	global_load_dword v237, v[240:241], off offset:576
	global_load_dword v238, v[240:241], off offset:640
	global_load_dword v239, v[240:241], off offset:704
	v_mov_b32_e32 v127, 0
	s_andn2_b64 vcc, exec, s[6:7]
	v_mov_b32_e32 v126, v127
	v_mov_b32_e32 v125, v127
	v_mov_b32_e32 v124, v127
	v_mov_b32_e32 v119, v127
	v_mov_b32_e32 v118, v127
	v_mov_b32_e32 v117, v127
	v_mov_b32_e32 v116, v127
	v_mov_b32_e32 v111, v127
	v_mov_b32_e32 v110, v127
	v_mov_b32_e32 v109, v127
	v_mov_b32_e32 v108, v127
	v_mov_b32_e32 v103, v127
	v_mov_b32_e32 v102, v127
	v_mov_b32_e32 v101, v127
	v_mov_b32_e32 v100, v127
	v_mov_b32_e32 v95, v127
	v_mov_b32_e32 v94, v127
	v_mov_b32_e32 v93, v127
	v_mov_b32_e32 v92, v127
	v_mov_b32_e32 v87, v127
	v_mov_b32_e32 v86, v127
	v_mov_b32_e32 v85, v127
	v_mov_b32_e32 v84, v127
	v_mov_b32_e32 v79, v127
	v_mov_b32_e32 v78, v127
	v_mov_b32_e32 v77, v127
	v_mov_b32_e32 v76, v127
	v_mov_b32_e32 v71, v127
	v_mov_b32_e32 v70, v127
	v_mov_b32_e32 v69, v127
	v_mov_b32_e32 v68, v127
	v_mov_b32_e32 v123, v127
	v_mov_b32_e32 v122, v127
	v_mov_b32_e32 v121, v127
	v_mov_b32_e32 v120, v127
	v_mov_b32_e32 v115, v127
	v_mov_b32_e32 v114, v127
	v_mov_b32_e32 v113, v127
	v_mov_b32_e32 v112, v127
	v_mov_b32_e32 v107, v127
	v_mov_b32_e32 v106, v127
	v_mov_b32_e32 v105, v127
	v_mov_b32_e32 v104, v127
	v_mov_b32_e32 v99, v127
	v_mov_b32_e32 v98, v127
	v_mov_b32_e32 v97, v127
	v_mov_b32_e32 v96, v127
	v_mov_b32_e32 v91, v127
	v_mov_b32_e32 v90, v127
	v_mov_b32_e32 v89, v127
	v_mov_b32_e32 v88, v127
	v_mov_b32_e32 v83, v127
	v_mov_b32_e32 v82, v127
	v_mov_b32_e32 v81, v127
	v_mov_b32_e32 v80, v127
	v_mov_b32_e32 v75, v127
	v_mov_b32_e32 v74, v127
	v_mov_b32_e32 v73, v127
	v_mov_b32_e32 v72, v127
	v_mov_b32_e32 v67, v127
	v_mov_b32_e32 v66, v127
	v_mov_b32_e32 v65, v127
	v_mov_b32_e32 v64, v127
	v_mov_b32_e32 v63, v127
	v_mov_b32_e32 v62, v127
	v_mov_b32_e32 v61, v127
	v_mov_b32_e32 v60, v127
	v_mov_b32_e32 v55, v127
	v_mov_b32_e32 v54, v127
	v_mov_b32_e32 v53, v127
	v_mov_b32_e32 v52, v127
	v_mov_b32_e32 v47, v127
	v_mov_b32_e32 v46, v127
	v_mov_b32_e32 v45, v127
	v_mov_b32_e32 v44, v127
	v_mov_b32_e32 v39, v127
	v_mov_b32_e32 v38, v127
	v_mov_b32_e32 v37, v127
	v_mov_b32_e32 v36, v127
	v_mov_b32_e32 v31, v127
	v_mov_b32_e32 v30, v127
	v_mov_b32_e32 v29, v127
	v_mov_b32_e32 v28, v127
	v_mov_b32_e32 v23, v127
	v_mov_b32_e32 v22, v127
	v_mov_b32_e32 v21, v127
	v_mov_b32_e32 v20, v127
	v_mov_b32_e32 v15, v127
	v_mov_b32_e32 v14, v127
	v_mov_b32_e32 v13, v127
	v_mov_b32_e32 v12, v127
	v_mov_b32_e32 v7, v127
	v_mov_b32_e32 v6, v127
	v_mov_b32_e32 v5, v127
	v_mov_b32_e32 v4, v127
	v_mov_b32_e32 v59, v127
	v_mov_b32_e32 v58, v127
	v_mov_b32_e32 v57, v127
	v_mov_b32_e32 v56, v127
	v_mov_b32_e32 v51, v127
	v_mov_b32_e32 v50, v127
	v_mov_b32_e32 v49, v127
	v_mov_b32_e32 v48, v127
	v_mov_b32_e32 v43, v127
	v_mov_b32_e32 v42, v127
	v_mov_b32_e32 v41, v127
	v_mov_b32_e32 v40, v127
	v_mov_b32_e32 v35, v127
	v_mov_b32_e32 v34, v127
	v_mov_b32_e32 v33, v127
	v_mov_b32_e32 v32, v127
	v_mov_b32_e32 v27, v127
	v_mov_b32_e32 v26, v127
	v_mov_b32_e32 v25, v127
	v_mov_b32_e32 v24, v127
	v_mov_b32_e32 v19, v127
	v_mov_b32_e32 v18, v127
	v_mov_b32_e32 v17, v127
	v_mov_b32_e32 v16, v127
	v_mov_b32_e32 v11, v127
	v_mov_b32_e32 v10, v127
	v_mov_b32_e32 v9, v127
	v_mov_b32_e32 v8, v127
	v_mov_b32_e32 v3, v127
	v_mov_b32_e32 v2, v127
	v_mov_b32_e32 v1, v127
	v_mov_b32_e32 v0, v127
	s_cbranch_vccnz .LBB0_1197
	s_add_u32 s24, s24, 0x40080
	s_addc_u32 s25, s25, 0
	s_add_u32 s11, s26, 0x100
	v_mov_b32_e32 v0, 0
	s_addc_u32 s13, s27, 0
	s_mov_b32 s26, 0
	v_mov_b32_e32 v1, v0
	v_mov_b32_e32 v2, v0
	v_mov_b32_e32 v3, v0
	v_mov_b32_e32 v8, v0
	v_mov_b32_e32 v9, v0
	v_mov_b32_e32 v10, v0
	v_mov_b32_e32 v11, v0
	v_mov_b32_e32 v16, v0
	v_mov_b32_e32 v17, v0
	v_mov_b32_e32 v18, v0
	v_mov_b32_e32 v19, v0
	v_mov_b32_e32 v24, v0
	v_mov_b32_e32 v25, v0
	v_mov_b32_e32 v26, v0
	v_mov_b32_e32 v27, v0
	v_mov_b32_e32 v32, v0
	v_mov_b32_e32 v33, v0
	v_mov_b32_e32 v34, v0
	v_mov_b32_e32 v35, v0
	v_mov_b32_e32 v40, v0
	v_mov_b32_e32 v41, v0
	v_mov_b32_e32 v42, v0
	v_mov_b32_e32 v43, v0
	v_mov_b32_e32 v48, v0
	v_mov_b32_e32 v49, v0
	v_mov_b32_e32 v50, v0
	v_mov_b32_e32 v51, v0
	v_mov_b32_e32 v56, v0
	v_mov_b32_e32 v57, v0
	v_mov_b32_e32 v58, v0
	v_mov_b32_e32 v59, v0
	v_mov_b32_e32 v4, v0
	v_mov_b32_e32 v5, v0
	v_mov_b32_e32 v6, v0
	v_mov_b32_e32 v7, v0
	v_mov_b32_e32 v12, v0
	v_mov_b32_e32 v13, v0
	v_mov_b32_e32 v14, v0
	v_mov_b32_e32 v15, v0
	v_mov_b32_e32 v20, v0
	v_mov_b32_e32 v21, v0
	v_mov_b32_e32 v22, v0
	v_mov_b32_e32 v23, v0
	v_mov_b32_e32 v28, v0
	v_mov_b32_e32 v29, v0
	v_mov_b32_e32 v30, v0
	v_mov_b32_e32 v31, v0
	v_mov_b32_e32 v36, v0
	v_mov_b32_e32 v37, v0
	v_mov_b32_e32 v38, v0
	v_mov_b32_e32 v39, v0
	v_mov_b32_e32 v44, v0
	v_mov_b32_e32 v45, v0
	v_mov_b32_e32 v46, v0
	v_mov_b32_e32 v47, v0
	v_mov_b32_e32 v52, v0
	v_mov_b32_e32 v53, v0
	v_mov_b32_e32 v54, v0
	v_mov_b32_e32 v55, v0
	v_mov_b32_e32 v60, v0
	v_mov_b32_e32 v61, v0
	v_mov_b32_e32 v62, v0
	v_mov_b32_e32 v63, v0
	v_mov_b32_e32 v64, v0
	v_mov_b32_e32 v65, v0
	v_mov_b32_e32 v66, v0
	v_mov_b32_e32 v67, v0
	v_mov_b32_e32 v72, v0
	v_mov_b32_e32 v73, v0
	v_mov_b32_e32 v74, v0
	v_mov_b32_e32 v75, v0
	v_mov_b32_e32 v80, v0
	v_mov_b32_e32 v81, v0
	v_mov_b32_e32 v82, v0
	v_mov_b32_e32 v83, v0
	v_mov_b32_e32 v88, v0
	v_mov_b32_e32 v89, v0
	v_mov_b32_e32 v90, v0
	v_mov_b32_e32 v91, v0
	v_mov_b32_e32 v96, v0
	v_mov_b32_e32 v97, v0
	v_mov_b32_e32 v98, v0
	v_mov_b32_e32 v99, v0
	v_mov_b32_e32 v104, v0
	v_mov_b32_e32 v105, v0
	v_mov_b32_e32 v106, v0
	v_mov_b32_e32 v107, v0
	v_mov_b32_e32 v112, v0
	v_mov_b32_e32 v113, v0
	v_mov_b32_e32 v114, v0
	v_mov_b32_e32 v115, v0
	v_mov_b32_e32 v120, v0
	v_mov_b32_e32 v121, v0
	v_mov_b32_e32 v122, v0
	v_mov_b32_e32 v123, v0
	v_mov_b32_e32 v68, v0
	v_mov_b32_e32 v69, v0
	v_mov_b32_e32 v70, v0
	v_mov_b32_e32 v71, v0
	v_mov_b32_e32 v76, v0
	v_mov_b32_e32 v77, v0
	v_mov_b32_e32 v78, v0
	v_mov_b32_e32 v79, v0
	v_mov_b32_e32 v84, v0
	v_mov_b32_e32 v85, v0
	v_mov_b32_e32 v86, v0
	v_mov_b32_e32 v87, v0
	v_mov_b32_e32 v92, v0
	v_mov_b32_e32 v93, v0
	v_mov_b32_e32 v94, v0
	v_mov_b32_e32 v95, v0
	v_mov_b32_e32 v100, v0
	v_mov_b32_e32 v101, v0
	v_mov_b32_e32 v102, v0
	v_mov_b32_e32 v103, v0
	v_mov_b32_e32 v108, v0
	v_mov_b32_e32 v109, v0
	v_mov_b32_e32 v110, v0
	v_mov_b32_e32 v111, v0
	v_mov_b32_e32 v116, v0
	v_mov_b32_e32 v117, v0
	v_mov_b32_e32 v118, v0
	v_mov_b32_e32 v119, v0
	v_mov_b32_e32 v124, v0
	v_mov_b32_e32 v125, v0
	v_mov_b32_e32 v126, v0
	v_mov_b32_e32 v127, v0

; __device__ __forceinline__ float sigmoidf_(float x) { return __builtin_amdgcn_rcpf(1.f + ex2(-x * LOG2E)); }
; __device__ __forceinline__ void load_rs(float (&rs)[2][4], const float* ssx, int row0) {
;     ...
; #pragma unroll
;     for (int ai = 0; ai < 2; ++ai)
; #pragma unroll
;         for (int m = 0; m < 4; ++m) rs[ai][m] = __builtin_amdgcn_rsqf(rs[ai][m] * (1.f / 1024.f) + EPS);
; }
;     __device__ __forceinline__ void operator()(const Acc& acc, const Unit& u, int wr, int wc, int fr, int fq) const {
;     ...
;         const float* ssx = SSP(l, SS_FFN); bf16_t* HF = (bf16_t*)(ws + WS_HF);
;         float rsv[2][4]; load_rs(rsv, ssx, u.pm * 256 + wr * 64 + fr);
; #pragma unroll
;         for (int ai = 0; ai < 2; ++ai)
; #pragma unroll
;             for (int m = 0; m < 4; ++m) {
;                 const int row = u.pm * 256 + ai * 128 + wr * 64 + m * 16 + fr;
;                 const float rs = rsv[ai][m];
;                 float o[8];
; #pragma unroll
;                 for (int n = 0; n < 2; ++n)
; #pragma unroll
;                     for (int j = 0; j < 4; ++j) { const float g = acc[ai][0][m][n][j] * rs, up = acc[ai][1][m][n][j] * rs; o[4 * n + j] = g * sigmoidf_(g) * up; }
;                 st16_nt(HF + (size_t)row * FFH + 128 * u.pn + 32 * wc + 8 * fq, o);
;             }
.LBB0_1199:
	s_mov_b64 s[20:21], s[2:3]
	s_add_u32 s22, s20, s36
	v_lshl_add_u32 v140, s18, 8, v143
	s_addc_u32 s23, s21, 0
	v_ashrrev_i32_e32 v141, 31, v140
	v_lshl_add_u64 v[144:145], v[140:141], 2, s[22:23]
	s_nop 0
	s_lshl_b32 s18, s19, 7
	s_ashr_i32 s19, s18, 31
	s_lshl_b64 s[18:19], s[18:19], 1
	s_add_u32 s11, s20, s18
	s_addc_u32 s13, s21, s19
	s_add_u32 s18, s11, s55
	s_addc_u32 s19, s13, 0
	s_andn2_b64 vcc, exec, s[0:1]
	v_fmamk_f32 v141, v232, 0x3a800000, v212
	v_rsq_f32_e32 v158, v141
	v_fmamk_f32 v141, v233, 0x3a800000, v212
	v_rsq_f32_e32 v166, v141
	v_fmamk_f32 v141, v234, 0x3a800000, v212
	v_rsq_f32_e32 v154, v141
	v_fmamk_f32 v141, v235, 0x3a800000, v212
	v_rsq_f32_e32 v152, v141
	v_fmamk_f32 v141, v236, 0x3a800000, v212
	v_rsq_f32_e32 v150, v141
	v_fmamk_f32 v141, v237, 0x3a800000, v212
	v_rsq_f32_e32 v148, v141
	v_fmamk_f32 v141, v238, 0x3a800000, v212
	v_rsq_f32_e32 v146, v141
	v_fmamk_f32 v141, v239, 0x3a800000, v212
	v_pk_mul_f32 v[124:125], v[124:125], v[158:159] op_sel_hi:[1,0]
	v_rsq_f32_e32 v142, v141
	v_mul_f32_e32 v141, 0xbfb8aa3b, v124
	v_exp_f32_e32 v141, v141
	v_pk_mul_f32 v[120:121], v[120:121], v[158:159] op_sel_hi:[1,0]
	v_pk_mul_f32 v[122:123], v[122:123], v[158:159] op_sel_hi:[1,0]
	v_pk_mul_f32 v[116:117], v[116:117], v[158:159] op_sel_hi:[1,0]
	v_add_f32_e32 v141, 1.0, v141
	v_rcp_f32_e32 v168, v141
	v_mul_f32_e32 v141, 0xbfb8aa3b, v125
	v_exp_f32_e32 v141, v141
	v_pk_mul_f32 v[112:113], v[112:113], v[158:159] op_sel_hi:[1,0]
	v_lshl_add_u64 v[144:145], s[18:19], 0, v[156:157]
	s_mov_b64 s[18:19], 0x6000000
	v_add_f32_e32 v141, 1.0, v141
	v_rcp_f32_e32 v169, v141
	v_pk_mul_f32 v[114:115], v[114:115], v[158:159] op_sel_hi:[1,0]
	v_lshl_add_u64 v[144:145], v[144:145], 0, s[18:19]
	v_pk_mul_f32 v[108:109], v[108:109], v[166:167] op_sel_hi:[1,0]
	v_pk_mul_f32 v[124:125], v[124:125], v[168:169]
	v_pk_mul_f32 v[104:105], v[104:105], v[166:167] op_sel_hi:[1,0]
	v_pk_mul_f32 v[120:121], v[120:121], v[124:125]
	v_pk_mul_f32 v[124:125], v[126:127], v[158:159] op_sel_hi:[1,0]
	v_pk_mul_f32 v[106:107], v[106:107], v[166:167] op_sel_hi:[1,0]
	v_mul_f32_e32 v126, 0xbfb8aa3b, v124
	v_mul_f32_e32 v127, 0xbfb8aa3b, v125
	v_exp_f32_e32 v126, v126
	v_exp_f32_e32 v127, v127
	v_pk_mul_f32 v[100:101], v[100:101], v[166:167] op_sel_hi:[1,0]
	v_pk_mul_f32 v[96:97], v[96:97], v[166:167] op_sel_hi:[1,0]
	v_add_f32_e32 v126, 1.0, v126
	v_add_f32_e32 v127, 1.0, v127
	v_rcp_f32_e32 v126, v126
	v_rcp_f32_e32 v127, v127
	v_pk_mul_f32 v[98:99], v[98:99], v[166:167] op_sel_hi:[1,0]
	v_pk_mul_f32 v[92:93], v[92:93], v[154:155] op_sel_hi:[1,0]
	v_pk_mul_f32 v[88:89], v[88:89], v[154:155] op_sel_hi:[1,0]
	v_pk_mul_f32 v[124:125], v[124:125], v[126:127]
	v_pk_mul_f32 v[90:91], v[90:91], v[154:155] op_sel_hi:[1,0]
	v_pk_mul_f32 v[122:123], v[122:123], v[124:125]
	v_mul_f32_e32 v124, 0xbfb8aa3b, v116
	v_mul_f32_e32 v125, 0xbfb8aa3b, v117
	v_exp_f32_e32 v124, v124
	v_exp_f32_e32 v125, v125
	v_pk_mul_f32 v[84:85], v[84:85], v[154:155] op_sel_hi:[1,0]
	v_pk_mul_f32 v[80:81], v[80:81], v[154:155] op_sel_hi:[1,0]
	v_add_f32_e32 v124, 1.0, v124
	v_add_f32_e32 v125, 1.0, v125
	v_rcp_f32_e32 v124, v124
	v_rcp_f32_e32 v125, v125
	v_pk_mul_f32 v[82:83], v[82:83], v[154:155] op_sel_hi:[1,0]
	v_pk_mul_f32 v[76:77], v[76:77], v[152:153] op_sel_hi:[1,0]
	v_pk_mul_f32 v[72:73], v[72:73], v[152:153] op_sel_hi:[1,0]
	v_pk_mul_f32 v[116:117], v[116:117], v[124:125]
	v_mad_i64_i32 v[124:125], s[18:19], v140, s86, v[144:145]
	v_pk_mul_f32 v[116:117], v[112:113], v[116:117]
	v_pk_mul_f32 v[112:113], v[118:119], v[158:159] op_sel_hi:[1,0]
	v_pk_mul_f32 v[74:75], v[74:75], v[152:153] op_sel_hi:[1,0]
	v_mul_f32_e32 v118, 0xbfb8aa3b, v112
	v_mul_f32_e32 v119, 0xbfb8aa3b, v113
	v_exp_f32_e32 v118, v118
	v_exp_f32_e32 v119, v119
	v_pk_mul_f32 v[68:69], v[68:69], v[152:153] op_sel_hi:[1,0]
	v_pk_mul_f32 v[64:65], v[64:65], v[152:153] op_sel_hi:[1,0]
	v_add_f32_e32 v118, 1.0, v118
	v_add_f32_e32 v119, 1.0, v119
	v_rcp_f32_e32 v118, v118
	v_rcp_f32_e32 v119, v119
	v_pk_mul_f32 v[66:67], v[66:67], v[152:153] op_sel_hi:[1,0]
	v_pk_mul_f32 v[60:61], v[60:61], v[150:151] op_sel_hi:[1,0]
	v_pk_mul_f32 v[56:57], v[56:57], v[150:151] op_sel_hi:[1,0]
	v_pk_mul_f32 v[112:113], v[112:113], v[118:119]
	v_pk_mul_f32 v[58:59], v[58:59], v[150:151] op_sel_hi:[1,0]
	v_pk_mul_f32 v[118:119], v[114:115], v[112:113]
	v_cvt_pk_bf16_f32 v112, v120, v121
	v_cvt_pk_bf16_f32 v113, v122, v123
	v_cvt_pk_bf16_f32 v114, v116, v117
	v_cvt_pk_bf16_f32 v115, v118, v119
	global_store_dwordx4 v[124:125], v[112:115], off nt
	v_pk_mul_f32 v[52:53], v[52:53], v[150:151] op_sel_hi:[1,0]
	v_pk_mul_f32 v[48:49], v[48:49], v[150:151] op_sel_hi:[1,0]
	v_mul_f32_e32 v112, 0xbfb8aa3b, v108
	v_mul_f32_e32 v113, 0xbfb8aa3b, v109
	v_exp_f32_e32 v112, v112
	v_exp_f32_e32 v113, v113
	v_pk_mul_f32 v[50:51], v[50:51], v[150:151] op_sel_hi:[1,0]
	v_pk_mul_f32 v[44:45], v[44:45], v[148:149] op_sel_hi:[1,0]
	v_add_f32_e32 v112, 1.0, v112
	v_add_f32_e32 v113, 1.0, v113
	v_rcp_f32_e32 v112, v112
	v_rcp_f32_e32 v113, v113
	v_pk_mul_f32 v[40:41], v[40:41], v[148:149] op_sel_hi:[1,0]
	v_pk_mul_f32 v[42:43], v[42:43], v[148:149] op_sel_hi:[1,0]
	v_pk_mul_f32 v[36:37], v[36:37], v[148:149] op_sel_hi:[1,0]
	v_pk_mul_f32 v[108:109], v[108:109], v[112:113]
	v_pk_mul_f32 v[32:33], v[32:33], v[148:149] op_sel_hi:[1,0]
	v_pk_mul_f32 v[104:105], v[104:105], v[108:109]
	v_pk_mul_f32 v[108:109], v[110:111], v[166:167] op_sel_hi:[1,0]
	v_pk_mul_f32 v[34:35], v[34:35], v[148:149] op_sel_hi:[1,0]
	v_mul_f32_e32 v110, 0xbfb8aa3b, v108
	v_mul_f32_e32 v111, 0xbfb8aa3b, v109
	v_exp_f32_e32 v110, v110
	v_exp_f32_e32 v111, v111
; __device__ __forceinline__ float sigmoidf_(float x) { return __builtin_amdgcn_rcpf(1.f + ex2(-x * LOG2E)); }
;     __device__ __forceinline__ void operator()(const Acc& acc, const Unit& u, int wr, int wc, int fr, int fq) const {
;     ...
;                 float o[8];
; #pragma unroll
;                 for (int n = 0; n < 2; ++n)
; #pragma unroll
;                     for (int j = 0; j < 4; ++j) { const float g = acc[ai][0][m][n][j] * rs, up = acc[ai][1][m][n][j] * rs; o[4 * n + j] = g * sigmoidf_(g) * up; }
;                 st16_nt(HF + (size_t)row * FFH + 128 * u.pn + 32 * wc + 8 * fq, o);
;             }
	v_pk_mul_f32 v[28:29], v[28:29], v[146:147] op_sel_hi:[1,0]
	v_pk_mul_f32 v[24:25], v[24:25], v[146:147] op_sel_hi:[1,0]
	v_add_f32_e32 v110, 1.0, v110
	v_add_f32_e32 v111, 1.0, v111
	v_rcp_f32_e32 v110, v110
	v_rcp_f32_e32 v111, v111
	v_pk_mul_f32 v[26:27], v[26:27], v[146:147] op_sel_hi:[1,0]
	v_pk_mul_f32 v[20:21], v[20:21], v[146:147] op_sel_hi:[1,0]
	v_pk_mul_f32 v[16:17], v[16:17], v[146:147] op_sel_hi:[1,0]
	v_pk_mul_f32 v[108:109], v[108:109], v[110:111]
	v_pk_mul_f32 v[18:19], v[18:19], v[146:147] op_sel_hi:[1,0]
	v_pk_mul_f32 v[106:107], v[106:107], v[108:109]
	v_mul_f32_e32 v108, 0xbfb8aa3b, v100
	v_mul_f32_e32 v109, 0xbfb8aa3b, v101
	v_exp_f32_e32 v108, v108
	v_exp_f32_e32 v109, v109
	v_pk_mul_f32 v[12:13], v[12:13], v[142:143] op_sel_hi:[1,0]
	v_pk_mul_f32 v[8:9], v[8:9], v[142:143] op_sel_hi:[1,0]
	v_add_f32_e32 v108, 1.0, v108
	v_add_f32_e32 v109, 1.0, v109
	v_rcp_f32_e32 v108, v108
	v_rcp_f32_e32 v109, v109
	v_pk_mul_f32 v[10:11], v[10:11], v[142:143] op_sel_hi:[1,0]
	v_pk_mul_f32 v[4:5], v[4:5], v[142:143] op_sel_hi:[1,0]
	v_pk_mul_f32 v[0:1], v[0:1], v[142:143] op_sel_hi:[1,0]
	v_pk_mul_f32 v[100:101], v[100:101], v[108:109]
	v_pk_mul_f32 v[2:3], v[2:3], v[142:143] op_sel_hi:[1,0]
	v_pk_mul_f32 v[100:101], v[96:97], v[100:101]
	v_pk_mul_f32 v[96:97], v[102:103], v[166:167] op_sel_hi:[1,0]
	s_nop 0
	v_mul_f32_e32 v102, 0xbfb8aa3b, v96
	v_mul_f32_e32 v103, 0xbfb8aa3b, v97
	v_exp_f32_e32 v102, v102
	v_exp_f32_e32 v103, v103
	v_add_f32_e32 v102, 1.0, v102
	v_add_f32_e32 v103, 1.0, v103
	v_rcp_f32_e32 v102, v102
	v_rcp_f32_e32 v103, v103
	s_nop 0
	v_pk_mul_f32 v[96:97], v[96:97], v[102:103]
	s_nop 0
	v_pk_mul_f32 v[102:103], v[98:99], v[96:97]
	v_or_b32_e32 v96, 16, v140
	v_mad_i64_i32 v[108:109], s[18:19], v96, s86, v[144:145]
	v_cvt_pk_bf16_f32 v96, v104, v105
	v_cvt_pk_bf16_f32 v97, v106, v107
	v_cvt_pk_bf16_f32 v98, v100, v101
	v_cvt_pk_bf16_f32 v99, v102, v103
	global_store_dwordx4 v[108:109], v[96:99], off nt
	s_nop 1
	v_mul_f32_e32 v96, 0xbfb8aa3b, v92
	v_mul_f32_e32 v97, 0xbfb8aa3b, v93
	v_exp_f32_e32 v96, v96
	v_exp_f32_e32 v97, v97
	v_add_f32_e32 v96, 1.0, v96
	v_add_f32_e32 v97, 1.0, v97
	v_rcp_f32_e32 v96, v96
	v_rcp_f32_e32 v97, v97
	s_nop 0
	v_pk_mul_f32 v[92:93], v[92:93], v[96:97]
	s_nop 0
	v_pk_mul_f32 v[88:89], v[88:89], v[92:93]
	v_pk_mul_f32 v[92:93], v[94:95], v[154:155] op_sel_hi:[1,0]
	s_nop 0
	v_mul_f32_e32 v94, 0xbfb8aa3b, v92
	v_mul_f32_e32 v95, 0xbfb8aa3b, v93
	v_exp_f32_e32 v94, v94
	v_exp_f32_e32 v95, v95
	v_add_f32_e32 v94, 1.0, v94
	v_add_f32_e32 v95, 1.0, v95
	v_rcp_f32_e32 v94, v94
	v_rcp_f32_e32 v95, v95
	s_nop 0
	v_pk_mul_f32 v[92:93], v[92:93], v[94:95]
	s_nop 0
	v_pk_mul_f32 v[90:91], v[90:91], v[92:93]
	v_mul_f32_e32 v92, 0xbfb8aa3b, v84
	v_mul_f32_e32 v93, 0xbfb8aa3b, v85
	v_exp_f32_e32 v92, v92
	v_exp_f32_e32 v93, v93
	v_add_f32_e32 v92, 1.0, v92
	v_add_f32_e32 v93, 1.0, v93
	v_rcp_f32_e32 v92, v92
	v_rcp_f32_e32 v93, v93
	s_nop 0
	v_pk_mul_f32 v[84:85], v[84:85], v[92:93]
	s_nop 0
	v_pk_mul_f32 v[84:85], v[80:81], v[84:85]
	v_pk_mul_f32 v[80:81], v[86:87], v[154:155] op_sel_hi:[1,0]
	s_nop 0
	v_mul_f32_e32 v86, 0xbfb8aa3b, v80
	v_mul_f32_e32 v87, 0xbfb8aa3b, v81
	v_exp_f32_e32 v86, v86
	v_exp_f32_e32 v87, v87
	v_add_f32_e32 v86, 1.0, v86
	v_add_f32_e32 v87, 1.0, v87
	v_rcp_f32_e32 v86, v86
	v_rcp_f32_e32 v87, v87
	s_nop 0
	v_pk_mul_f32 v[80:81], v[80:81], v[86:87]
	s_nop 0
	v_pk_mul_f32 v[86:87], v[82:83], v[80:81]
	v_or_b32_e32 v80, 32, v140
	v_mad_i64_i32 v[92:93], s[18:19], v80, s86, v[144:145]
	v_cvt_pk_bf16_f32 v80, v88, v89
	v_cvt_pk_bf16_f32 v81, v90, v91
	v_cvt_pk_bf16_f32 v82, v84, v85
	v_cvt_pk_bf16_f32 v83, v86, v87
	global_store_dwordx4 v[92:93], v[80:83], off nt
	s_nop 1
	v_mul_f32_e32 v80, 0xbfb8aa3b, v76
	v_mul_f32_e32 v81, 0xbfb8aa3b, v77
	v_exp_f32_e32 v80, v80
	v_exp_f32_e32 v81, v81
	v_add_f32_e32 v80, 1.0, v80
	v_add_f32_e32 v81, 1.0, v81
	v_rcp_f32_e32 v80, v80
	v_rcp_f32_e32 v81, v81
	s_nop 0
	v_pk_mul_f32 v[76:77], v[76:77], v[80:81]
	s_nop 0
	v_pk_mul_f32 v[72:73], v[72:73], v[76:77]
	v_pk_mul_f32 v[76:77], v[78:79], v[152:153] op_sel_hi:[1,0]
	s_nop 0
	v_mul_f32_e32 v78, 0xbfb8aa3b, v76
	v_mul_f32_e32 v79, 0xbfb8aa3b, v77
	v_exp_f32_e32 v78, v78
	v_exp_f32_e32 v79, v79
	v_add_f32_e32 v78, 1.0, v78
	v_add_f32_e32 v79, 1.0, v79
	v_rcp_f32_e32 v78, v78
	v_rcp_f32_e32 v79, v79
	s_nop 0
	v_pk_mul_f32 v[76:77], v[76:77], v[78:79]
	s_nop 0
	v_pk_mul_f32 v[74:75], v[74:75], v[76:77]
	v_mul_f32_e32 v76, 0xbfb8aa3b, v68
	v_mul_f32_e32 v77, 0xbfb8aa3b, v69
	v_exp_f32_e32 v76, v76
	v_exp_f32_e32 v77, v77
	v_add_f32_e32 v76, 1.0, v76
	v_add_f32_e32 v77, 1.0, v77
	v_rcp_f32_e32 v76, v76
	v_rcp_f32_e32 v77, v77
	s_nop 0
	v_pk_mul_f32 v[68:69], v[68:69], v[76:77]
	s_nop 0
	v_pk_mul_f32 v[68:69], v[64:65], v[68:69]
	v_pk_mul_f32 v[64:65], v[70:71], v[152:153] op_sel_hi:[1,0]
	s_nop 0
	v_mul_f32_e32 v70, 0xbfb8aa3b, v64
	v_mul_f32_e32 v71, 0xbfb8aa3b, v65
	v_exp_f32_e32 v70, v70
	v_exp_f32_e32 v71, v71
	v_add_f32_e32 v70, 1.0, v70
	v_add_f32_e32 v71, 1.0, v71
	v_rcp_f32_e32 v70, v70
	v_rcp_f32_e32 v71, v71
	s_nop 0
	v_pk_mul_f32 v[64:65], v[64:65], v[70:71]
	s_nop 0
	v_pk_mul_f32 v[70:71], v[66:67], v[64:65]
	v_or_b32_e32 v64, 48, v140
	v_mad_i64_i32 v[76:77], s[18:19], v64, s86, v[144:145]
	v_cvt_pk_bf16_f32 v64, v72, v73
	v_cvt_pk_bf16_f32 v65, v74, v75
	v_cvt_pk_bf16_f32 v66, v68, v69
	v_cvt_pk_bf16_f32 v67, v70, v71
	global_store_dwordx4 v[76:77], v[64:67], off nt
	s_nop 1
	v_mul_f32_e32 v64, 0xbfb8aa3b, v60
	v_mul_f32_e32 v65, 0xbfb8aa3b, v61
	v_exp_f32_e32 v64, v64
	v_exp_f32_e32 v65, v65
	v_add_u32_e32 v66, 0x80, v140
	v_add_f32_e32 v64, 1.0, v64
	v_add_f32_e32 v65, 1.0, v65
; __device__ __forceinline__ float sigmoidf_(float x) { return __builtin_amdgcn_rcpf(1.f + ex2(-x * LOG2E)); }
; #define PG8_BAR __builtin_amdgcn_s_barrier()
; template <class Epi, class SchedT, class HookT = NoHook>
; __device__ __forceinline__ void gemm_phase(LAS unsigned char* lds, const SchedT& S, const Epi& E, int wave_, const HookT& H = HookT()) {
;     ...
;         if (wr == 0) PG8_BAR;
;         E(acc, cur, wr, wc, fr, fq);
;         if (!has_next) break;
; #pragma unroll
;         for (int a = 0; a < 2; ++a)
; #pragma unroll
;             for (int b = 0; b < 2; ++b)
; #pragma unroll
;                 for (int m = 0; m < 4; ++m)
; #pragma unroll
;                     for (int n = 0; n < 2; ++n) acc[a][b][m][n] = (f32x4){0.f, 0.f, 0.f, 0.f};
;         cur = nxt; cA = nA; cB = nB; ++ui;
;         if (wr == 1) PG8_BAR;
;     __device__ __forceinline__ void operator()(const Acc& acc, const Unit& u, int wr, int wc, int fr, int fq) const {
;     ...
;                 float o[8];
; #pragma unroll
;                 for (int n = 0; n < 2; ++n)
; #pragma unroll
;                     for (int j = 0; j < 4; ++j) { const float g = acc[ai][0][m][n][j] * rs, up = acc[ai][1][m][n][j] * rs; o[4 * n + j] = g * sigmoidf_(g) * up; }
;                 st16_nt(HF + (size_t)row * FFH + 128 * u.pn + 32 * wc + 8 * fq, o);
;             }
	v_rcp_f32_e32 v64, v64
	v_rcp_f32_e32 v65, v65
	s_nop 0
	v_pk_mul_f32 v[60:61], v[60:61], v[64:65]
	s_nop 0
	v_pk_mul_f32 v[56:57], v[56:57], v[60:61]
	v_pk_mul_f32 v[60:61], v[62:63], v[150:151] op_sel_hi:[1,0]
	s_nop 0
	v_mul_f32_e32 v62, 0xbfb8aa3b, v60
	v_mul_f32_e32 v63, 0xbfb8aa3b, v61
	v_exp_f32_e32 v62, v62
	v_exp_f32_e32 v63, v63
	v_add_f32_e32 v62, 1.0, v62
	v_add_f32_e32 v63, 1.0, v63
	v_rcp_f32_e32 v62, v62
	v_rcp_f32_e32 v63, v63
	s_nop 0
	v_pk_mul_f32 v[60:61], v[60:61], v[62:63]
	s_nop 0
	v_pk_mul_f32 v[58:59], v[58:59], v[60:61]
	v_mul_f32_e32 v60, 0xbfb8aa3b, v52
	v_mul_f32_e32 v61, 0xbfb8aa3b, v53
	v_exp_f32_e32 v60, v60
	v_exp_f32_e32 v61, v61
	v_add_f32_e32 v60, 1.0, v60
	v_add_f32_e32 v61, 1.0, v61
	v_rcp_f32_e32 v60, v60
	v_rcp_f32_e32 v61, v61
	s_nop 0
	v_pk_mul_f32 v[52:53], v[52:53], v[60:61]
	s_nop 0
	v_pk_mul_f32 v[52:53], v[48:49], v[52:53]
	v_pk_mul_f32 v[48:49], v[54:55], v[150:151] op_sel_hi:[1,0]
	v_mad_i64_i32 v[60:61], s[18:19], v66, s86, v[144:145]
	v_mul_f32_e32 v54, 0xbfb8aa3b, v48
	v_mul_f32_e32 v55, 0xbfb8aa3b, v49
	v_exp_f32_e32 v54, v54
	v_exp_f32_e32 v55, v55
	v_add_f32_e32 v54, 1.0, v54
	v_add_f32_e32 v55, 1.0, v55
	v_rcp_f32_e32 v54, v54
	v_rcp_f32_e32 v55, v55
	s_nop 0
	v_pk_mul_f32 v[48:49], v[48:49], v[54:55]
	s_nop 0
	v_pk_mul_f32 v[54:55], v[50:51], v[48:49]
	v_cvt_pk_bf16_f32 v48, v56, v57
	v_cvt_pk_bf16_f32 v49, v58, v59
	v_cvt_pk_bf16_f32 v50, v52, v53
	v_cvt_pk_bf16_f32 v51, v54, v55
	global_store_dwordx4 v[60:61], v[48:51], off nt
	s_nop 1
	v_mul_f32_e32 v48, 0xbfb8aa3b, v44
	v_mul_f32_e32 v49, 0xbfb8aa3b, v45
	v_exp_f32_e32 v48, v48
	v_exp_f32_e32 v49, v49
	v_add_f32_e32 v48, 1.0, v48
	v_add_f32_e32 v49, 1.0, v49
	v_rcp_f32_e32 v48, v48
	v_rcp_f32_e32 v49, v49
	s_nop 0
	v_pk_mul_f32 v[44:45], v[44:45], v[48:49]
	s_nop 0
	v_pk_mul_f32 v[40:41], v[40:41], v[44:45]
	v_pk_mul_f32 v[44:45], v[46:47], v[148:149] op_sel_hi:[1,0]
	s_nop 0
	v_mul_f32_e32 v46, 0xbfb8aa3b, v44
	v_mul_f32_e32 v47, 0xbfb8aa3b, v45
	v_exp_f32_e32 v46, v46
	v_exp_f32_e32 v47, v47
	v_add_f32_e32 v46, 1.0, v46
	v_add_f32_e32 v47, 1.0, v47
	v_rcp_f32_e32 v46, v46
	v_rcp_f32_e32 v47, v47
	s_nop 0
	v_pk_mul_f32 v[44:45], v[44:45], v[46:47]
	s_nop 0
	v_pk_mul_f32 v[42:43], v[42:43], v[44:45]
	v_mul_f32_e32 v44, 0xbfb8aa3b, v36
	v_mul_f32_e32 v45, 0xbfb8aa3b, v37
	v_exp_f32_e32 v44, v44
	v_exp_f32_e32 v45, v45
	v_add_f32_e32 v44, 1.0, v44
	v_add_f32_e32 v45, 1.0, v45
	v_rcp_f32_e32 v44, v44
	v_rcp_f32_e32 v45, v45
	s_nop 0
	v_pk_mul_f32 v[36:37], v[36:37], v[44:45]
	s_nop 0
	v_pk_mul_f32 v[36:37], v[32:33], v[36:37]
	v_pk_mul_f32 v[32:33], v[38:39], v[148:149] op_sel_hi:[1,0]
	s_nop 0
	v_mul_f32_e32 v38, 0xbfb8aa3b, v32
	v_mul_f32_e32 v39, 0xbfb8aa3b, v33
	v_exp_f32_e32 v38, v38
	v_exp_f32_e32 v39, v39
	v_add_f32_e32 v38, 1.0, v38
	v_add_f32_e32 v39, 1.0, v39
	v_rcp_f32_e32 v38, v38
	v_rcp_f32_e32 v39, v39
	s_nop 0
	v_pk_mul_f32 v[32:33], v[32:33], v[38:39]
	s_nop 0
	v_pk_mul_f32 v[38:39], v[34:35], v[32:33]
	v_add_u32_e32 v32, 0x90, v140
	v_mad_i64_i32 v[44:45], s[18:19], v32, s86, v[144:145]
	v_cvt_pk_bf16_f32 v32, v40, v41
	v_cvt_pk_bf16_f32 v33, v42, v43
	v_cvt_pk_bf16_f32 v34, v36, v37
	v_cvt_pk_bf16_f32 v35, v38, v39
	global_store_dwordx4 v[44:45], v[32:35], off nt
	s_nop 1
	v_mul_f32_e32 v32, 0xbfb8aa3b, v28
	v_mul_f32_e32 v33, 0xbfb8aa3b, v29
	v_exp_f32_e32 v32, v32
	v_exp_f32_e32 v33, v33
	v_add_f32_e32 v32, 1.0, v32
	v_add_f32_e32 v33, 1.0, v33
	v_rcp_f32_e32 v32, v32
	v_rcp_f32_e32 v33, v33
	s_nop 0
	v_pk_mul_f32 v[28:29], v[28:29], v[32:33]
	s_nop 0
	v_pk_mul_f32 v[24:25], v[24:25], v[28:29]
	v_pk_mul_f32 v[28:29], v[30:31], v[146:147] op_sel_hi:[1,0]
	s_nop 0
	v_mul_f32_e32 v30, 0xbfb8aa3b, v28
	v_mul_f32_e32 v31, 0xbfb8aa3b, v29
	v_exp_f32_e32 v30, v30
	v_exp_f32_e32 v31, v31
	v_add_f32_e32 v30, 1.0, v30
	v_add_f32_e32 v31, 1.0, v31
	v_rcp_f32_e32 v30, v30
	v_rcp_f32_e32 v31, v31
	s_nop 0
	v_pk_mul_f32 v[28:29], v[28:29], v[30:31]
	s_nop 0
	v_pk_mul_f32 v[26:27], v[26:27], v[28:29]
	v_mul_f32_e32 v28, 0xbfb8aa3b, v20
	v_mul_f32_e32 v29, 0xbfb8aa3b, v21
	v_exp_f32_e32 v28, v28
	v_exp_f32_e32 v29, v29
	v_add_f32_e32 v28, 1.0, v28
	v_add_f32_e32 v29, 1.0, v29
	v_rcp_f32_e32 v28, v28
	v_rcp_f32_e32 v29, v29
	s_nop 0
	v_pk_mul_f32 v[20:21], v[20:21], v[28:29]
	s_nop 0
	v_pk_mul_f32 v[20:21], v[16:17], v[20:21]
	v_pk_mul_f32 v[16:17], v[22:23], v[146:147] op_sel_hi:[1,0]
	s_nop 0
	v_mul_f32_e32 v22, 0xbfb8aa3b, v16
	v_mul_f32_e32 v23, 0xbfb8aa3b, v17
	v_exp_f32_e32 v22, v22
	v_exp_f32_e32 v23, v23
	v_add_f32_e32 v22, 1.0, v22
	v_add_f32_e32 v23, 1.0, v23
	v_rcp_f32_e32 v22, v22
	v_rcp_f32_e32 v23, v23
	s_nop 0
	v_pk_mul_f32 v[16:17], v[16:17], v[22:23]
	s_nop 0
	v_pk_mul_f32 v[22:23], v[18:19], v[16:17]
	v_add_u32_e32 v16, 0xa0, v140
	v_mad_i64_i32 v[28:29], s[18:19], v16, s86, v[144:145]
	v_cvt_pk_bf16_f32 v16, v24, v25
	v_cvt_pk_bf16_f32 v17, v26, v27
	v_cvt_pk_bf16_f32 v18, v20, v21
	v_cvt_pk_bf16_f32 v19, v22, v23
	global_store_dwordx4 v[28:29], v[16:19], off nt
	s_nop 1
	v_mul_f32_e32 v16, 0xbfb8aa3b, v12
	v_mul_f32_e32 v17, 0xbfb8aa3b, v13
	v_exp_f32_e32 v16, v16
	v_exp_f32_e32 v17, v17
	v_add_f32_e32 v16, 1.0, v16
	v_add_f32_e32 v17, 1.0, v17
	v_rcp_f32_e32 v16, v16
	v_rcp_f32_e32 v17, v17
	s_nop 0
	v_pk_mul_f32 v[12:13], v[12:13], v[16:17]
	s_nop 0
	v_pk_mul_f32 v[8:9], v[8:9], v[12:13]
	v_pk_mul_f32 v[12:13], v[14:15], v[142:143] op_sel_hi:[1,0]
	s_nop 0
	v_mul_f32_e32 v14, 0xbfb8aa3b, v12
	v_mul_f32_e32 v15, 0xbfb8aa3b, v13
	v_exp_f32_e32 v14, v14
	v_exp_f32_e32 v15, v15
	v_add_f32_e32 v14, 1.0, v14
	v_add_f32_e32 v15, 1.0, v15
	v_rcp_f32_e32 v14, v14
	v_rcp_f32_e32 v15, v15
	s_nop 0
	v_pk_mul_f32 v[12:13], v[12:13], v[14:15]
	s_nop 0
	v_pk_mul_f32 v[10:11], v[10:11], v[12:13]
	v_mul_f32_e32 v12, 0xbfb8aa3b, v4
	v_mul_f32_e32 v13, 0xbfb8aa3b, v5
	v_exp_f32_e32 v12, v12
	v_exp_f32_e32 v13, v13
	v_add_f32_e32 v12, 1.0, v12
	v_add_f32_e32 v13, 1.0, v13
	v_rcp_f32_e32 v12, v12
	v_rcp_f32_e32 v13, v13
	s_nop 0
	v_pk_mul_f32 v[4:5], v[4:5], v[12:13]
	s_nop 0
	v_pk_mul_f32 v[4:5], v[0:1], v[4:5]
	v_pk_mul_f32 v[0:1], v[6:7], v[142:143] op_sel_hi:[1,0]
	s_nop 0
	v_mul_f32_e32 v6, 0xbfb8aa3b, v0
	v_mul_f32_e32 v7, 0xbfb8aa3b, v1
	v_exp_f32_e32 v6, v6
	v_exp_f32_e32 v7, v7
	v_add_f32_e32 v6, 1.0, v6
	v_add_f32_e32 v7, 1.0, v7
	v_rcp_f32_e32 v6, v6
	v_rcp_f32_e32 v7, v7
	s_nop 0
	v_pk_mul_f32 v[0:1], v[0:1], v[6:7]
	s_nop 0
	v_pk_mul_f32 v[6:7], v[2:3], v[0:1]
	v_add_u32_e32 v0, 0xb0, v140
	v_mad_i64_i32 v[12:13], s[18:19], v0, s86, v[144:145]
	v_cvt_pk_bf16_f32 v0, v8, v9
	v_cvt_pk_bf16_f32 v1, v10, v11
	v_cvt_pk_bf16_f32 v2, v4, v5
	v_cvt_pk_bf16_f32 v3, v6, v7
	s_mov_b64 s[18:19], -1
	global_store_dwordx4 v[12:13], v[0:3], off nt
	s_cbranch_vccnz .LBB0_1191
	s_andn2_b64 vcc, exec, s[4:5]
	s_cbranch_vccnz .LBB0_1190
	s_barrier
	s_branch .LBB0_1190
